# v84 + NSA top-n compare blocks VALU-only (v_min/v_cndmask, no SALU mask round trip) + attention-loop vmcnt(0) skip branches inverted
# baseline (speedup 1.0000x reference)
.LBB0_943:
	s_or_b64 exec, exec, s[4:5]
	v_add_u32_e32 v0, 0xa804, v197
	v_add_u32_e32 v2, 0xc904, v197
	ds_read2_b32 v[0:1], v0 offset1:1
	ds_read2_b32 v[2:3], v2 offset1:1
	v_add_u32_e32 v5, 0xea04, v197
	v_add_u32_e32 v8, 0x6304, v198
	ds_read2_b32 v[6:7], v5 offset1:1
	ds_read2_b32 v[8:9], v8 offset1:1
	ds_read_b32 v10, v197 offset:59916
	ds_read_b32 v11, v198 offset:25356
	v_cmp_gt_u32_e32 vcc, s2, v196
	s_waitcnt lgkmcnt(4)
	v_add_f32_e32 v0, v0, v2
	s_waitcnt lgkmcnt(3)
	v_add_f32_e32 v0, v0, v6
	s_waitcnt lgkmcnt(2)
	v_add_f32_e32 v0, v0, v8
	v_cndmask_b32_e32 v5, -1.0, v0, vcc
	v_add_u32_e32 v0, 12, v197
	v_add_f32_e32 v2, v1, v3
	ds_read2st64_b32 v[0:1], v0 offset0:168 offset1:201
	v_add_f32_e32 v2, v2, v7
	v_add_f32_e32 v2, v2, v9
	v_cmp_ge_u32_e32 vcc, s2, v200
	s_waitcnt lgkmcnt(0)
	v_add_f32_e32 v0, v0, v1
	v_add_f32_e32 v0, v0, v10
	v_cndmask_b32_e32 v6, -1.0, v2, vcc
	v_add_f32_e32 v0, v0, v11
	v_cmp_ge_u32_e32 vcc, s2, v201
	s_nop 1
	v_cndmask_b32_e32 v7, -1.0, v0, vcc
	v_and_b32_e32 v0, 64, v211
	v_cmp_gt_f32_e32 vcc, v5, v4
	v_add_u32_e32 v3, 64, v0
	s_nop 0
	v_cndmask_b32_e32 v0, v4, v5, vcc
	v_cndmask_b32_e32 v1, v196, v199, vcc
	v_cmp_gt_f32_e32 vcc, v6, v0
	s_nop 1
	v_cndmask_b32_e32 v0, v0, v6, vcc
	v_cndmask_b32_e32 v9, v1, v200, vcc
	v_cmp_gt_f32_e32 vcc, v7, v0
	s_nop 1
	v_cndmask_b32_e32 v8, v0, v7, vcc
	v_xor_b32_e32 v0, 1, v211
	v_cmp_lt_i32_e64 s[14:15], v0, v3
	s_nop 1
	v_cndmask_b32_e64 v0, v211, v0, s[14:15]
	v_lshlrev_b32_e32 v1, 2, v0
	s_nop 1
	v_mov_b32_dpp v2, v8 quad_perm:[1,0,3,2] row_mask:0xf bank_mask:0xf
	v_cndmask_b32_e32 v0, v9, v201, vcc
	s_nop 1
	v_mov_b32_dpp v9, v0 quad_perm:[1,0,3,2] row_mask:0xf bank_mask:0xf
	s_waitcnt lgkmcnt(1)
	v_cmp_lt_f32_e64 s[4:5], v8, v2
	v_cmp_eq_f32_e32 vcc, v8, v2
	s_waitcnt lgkmcnt(0)
	v_min_i32_e32 v242, v0, v9
	v_cndmask_b32_e64 v8, v8, v2, s[4:5]
	v_cndmask_b32_e64 v0, v0, v9, s[4:5]
	v_cndmask_b32_e32 v0, v0, v242, vcc
	v_xor_b32_e32 v2, 2, v211
	v_cmp_lt_i32_e32 vcc, v2, v3
	s_nop 1
	v_cndmask_b32_e32 v2, v211, v2, vcc
	v_lshlrev_b32_e32 v2, 2, v2
	s_nop 1
	v_mov_b32_dpp v10, v8 quad_perm:[2,3,0,1] row_mask:0xf bank_mask:0xf
	s_waitcnt lgkmcnt(1)
	s_nop 1
	v_mov_b32_dpp v9, v0 quad_perm:[2,3,0,1] row_mask:0xf bank_mask:0xf
	s_waitcnt lgkmcnt(1)
	v_cmp_lt_f32_e64 s[4:5], v8, v10
	v_cmp_eq_f32_e32 vcc, v8, v10
	s_waitcnt lgkmcnt(0)
	v_min_i32_e32 v242, v0, v9
	v_cndmask_b32_e64 v8, v8, v10, s[4:5]
	v_cndmask_b32_e64 v0, v0, v9, s[4:5]
	v_cndmask_b32_e32 v0, v0, v242, vcc
	s_waitcnt lgkmcnt(0)
	v_xor_b32_e32 v9, 4, v211
	v_cmp_lt_i32_e32 vcc, v9, v3
	s_nop 1
	v_cndmask_b32_e32 v3, v211, v9, vcc
	v_lshlrev_b32_e32 v3, 2, v3
	s_nop 1
	v_mov_b32_dpp v241, v8 row_half_mirror row_mask:0xf bank_mask:0xf
	s_nop 1
	v_mov_b32_dpp v10, v241 quad_perm:[3,2,1,0] row_mask:0xf bank_mask:0xf
	s_nop 1
	v_mov_b32_dpp v241, v0 row_half_mirror row_mask:0xf bank_mask:0xf
	s_nop 1
	v_mov_b32_dpp v9, v241 quad_perm:[3,2,1,0] row_mask:0xf bank_mask:0xf
	s_waitcnt lgkmcnt(1)
	v_cmp_lt_f32_e64 s[4:5], v8, v10
	v_cmp_eq_f32_e32 vcc, v8, v10
	s_waitcnt lgkmcnt(0)
	v_min_i32_e32 v242, v0, v9
	s_nop 0
	v_cndmask_b32_e64 v0, v0, v9, s[4:5]
	v_cndmask_b32_e32 v0, v0, v242, vcc
	v_cmp_ne_u32_e32 vcc, v196, v0
	s_nop 1
	v_cndmask_b32_e32 v8, -1.0, v4, vcc
	v_cmp_ne_u32_e32 vcc, v199, v0
	s_nop 1
	v_cndmask_b32_e32 v5, -1.0, v5, vcc
	v_cmp_ne_u32_e32 vcc, v200, v0
	s_nop 1
	v_cndmask_b32_e32 v6, -1.0, v6, vcc
	v_cmp_ne_u32_e32 vcc, v201, v0
	s_nop 1
	v_cndmask_b32_e32 v7, -1.0, v7, vcc
	v_cmp_gt_f32_e32 vcc, v5, v8
	s_nop 1
	v_cndmask_b32_e32 v4, v8, v5, vcc
	s_waitcnt lgkmcnt(0)
	v_cndmask_b32_e32 v9, v196, v199, vcc
	v_cmp_gt_f32_e32 vcc, v6, v4
	s_nop 1
	v_cndmask_b32_e32 v4, v4, v6, vcc
	v_cndmask_b32_e32 v11, v9, v200, vcc
	v_cmp_gt_f32_e32 vcc, v7, v4
	s_nop 1
	v_cndmask_b32_e32 v9, v4, v7, vcc
	s_nop 1
	v_mov_b32_dpp v10, v9 quad_perm:[1,0,3,2] row_mask:0xf bank_mask:0xf
	v_cndmask_b32_e32 v4, v11, v201, vcc
	s_nop 1
	v_mov_b32_dpp v11, v4 quad_perm:[1,0,3,2] row_mask:0xf bank_mask:0xf
	s_waitcnt lgkmcnt(1)
	v_cmp_lt_f32_e64 s[4:5], v9, v10
	v_cmp_eq_f32_e32 vcc, v9, v10
	s_waitcnt lgkmcnt(0)
	v_min_i32_e32 v242, v4, v11
	v_cndmask_b32_e64 v9, v9, v10, s[4:5]
	v_cndmask_b32_e64 v4, v4, v11, s[4:5]
	v_cndmask_b32_e32 v4, v4, v242, vcc
	s_waitcnt lgkmcnt(0)
	s_nop 1
	v_mov_b32_dpp v11, v9 quad_perm:[2,3,0,1] row_mask:0xf bank_mask:0xf
	s_nop 1
	v_mov_b32_dpp v10, v4 quad_perm:[2,3,0,1] row_mask:0xf bank_mask:0xf
	s_waitcnt lgkmcnt(1)
	v_cmp_lt_f32_e64 s[4:5], v9, v11
	v_cmp_eq_f32_e32 vcc, v9, v11
	s_waitcnt lgkmcnt(0)
	v_min_i32_e32 v242, v4, v10
	v_cndmask_b32_e64 v9, v9, v11, s[4:5]
	v_cndmask_b32_e64 v4, v4, v10, s[4:5]
	v_cndmask_b32_e32 v4, v4, v242, vcc
	s_nop 1
	v_mov_b32_dpp v241, v9 row_half_mirror row_mask:0xf bank_mask:0xf
	s_nop 1
	v_mov_b32_dpp v11, v241 quad_perm:[3,2,1,0] row_mask:0xf bank_mask:0xf
	s_waitcnt lgkmcnt(1)
	s_nop 1
	v_mov_b32_dpp v241, v4 row_half_mirror row_mask:0xf bank_mask:0xf
	s_nop 1
	v_mov_b32_dpp v10, v241 quad_perm:[3,2,1,0] row_mask:0xf bank_mask:0xf
	s_waitcnt lgkmcnt(1)
	v_cmp_lt_f32_e64 s[4:5], v9, v11
	v_cmp_eq_f32_e32 vcc, v9, v11
	s_waitcnt lgkmcnt(0)
	v_min_i32_e32 v242, v4, v10
	s_nop 0
	v_cndmask_b32_e64 v4, v4, v10, s[4:5]
	v_cndmask_b32_e32 v4, v4, v242, vcc
	v_cmp_ne_u32_e32 vcc, v196, v4
	s_nop 1
	v_cndmask_b32_e32 v8, -1.0, v8, vcc
	v_cmp_ne_u32_e32 vcc, v199, v4
	s_nop 1
	v_cndmask_b32_e32 v9, -1.0, v5, vcc
	v_cmp_ne_u32_e32 vcc, v200, v4
	s_nop 1
	v_cndmask_b32_e32 v6, -1.0, v6, vcc
	v_cmp_ne_u32_e32 vcc, v201, v4
	s_nop 1
	v_cndmask_b32_e32 v7, -1.0, v7, vcc
	v_cmp_gt_f32_e32 vcc, v9, v8
	s_nop 1
	v_cndmask_b32_e32 v5, v8, v9, vcc
	s_waitcnt lgkmcnt(0)
	v_cndmask_b32_e32 v10, v196, v199, vcc
	v_cmp_gt_f32_e32 vcc, v6, v5
	s_nop 1
	v_cndmask_b32_e32 v5, v5, v6, vcc
	v_cndmask_b32_e32 v12, v10, v200, vcc
	v_cmp_gt_f32_e32 vcc, v7, v5
	s_nop 1
	v_cndmask_b32_e32 v10, v5, v7, vcc
	s_nop 1
	v_mov_b32_dpp v11, v10 quad_perm:[1,0,3,2] row_mask:0xf bank_mask:0xf
	v_cndmask_b32_e32 v5, v12, v201, vcc
	s_nop 1
	v_mov_b32_dpp v12, v5 quad_perm:[1,0,3,2] row_mask:0xf bank_mask:0xf
	s_waitcnt lgkmcnt(1)
	v_cmp_lt_f32_e64 s[4:5], v10, v11
	v_cmp_eq_f32_e32 vcc, v10, v11
	s_waitcnt lgkmcnt(0)
	v_min_i32_e32 v242, v5, v12
	v_cndmask_b32_e64 v10, v10, v11, s[4:5]
	v_cndmask_b32_e64 v5, v5, v12, s[4:5]
	v_cndmask_b32_e32 v5, v5, v242, vcc
	s_waitcnt lgkmcnt(0)
	s_nop 1
	v_mov_b32_dpp v12, v10 quad_perm:[2,3,0,1] row_mask:0xf bank_mask:0xf
	s_nop 1
	v_mov_b32_dpp v11, v5 quad_perm:[2,3,0,1] row_mask:0xf bank_mask:0xf
	s_waitcnt lgkmcnt(1)
	v_cmp_lt_f32_e64 s[4:5], v10, v12
	v_cmp_eq_f32_e32 vcc, v10, v12
	s_waitcnt lgkmcnt(0)
	v_min_i32_e32 v242, v5, v11
	v_cndmask_b32_e64 v10, v10, v12, s[4:5]
	v_cndmask_b32_e64 v5, v5, v11, s[4:5]
	v_cndmask_b32_e32 v5, v5, v242, vcc
	s_nop 1
	v_mov_b32_dpp v241, v10 row_half_mirror row_mask:0xf bank_mask:0xf
	s_nop 1
	v_mov_b32_dpp v12, v241 quad_perm:[3,2,1,0] row_mask:0xf bank_mask:0xf
	s_waitcnt lgkmcnt(1)
	s_nop 1
	v_mov_b32_dpp v241, v5 row_half_mirror row_mask:0xf bank_mask:0xf
	s_nop 1
	v_mov_b32_dpp v11, v241 quad_perm:[3,2,1,0] row_mask:0xf bank_mask:0xf
	s_waitcnt lgkmcnt(1)
	v_cmp_lt_f32_e64 s[4:5], v10, v12
	v_cmp_eq_f32_e32 vcc, v10, v12
	s_waitcnt lgkmcnt(0)
	v_min_i32_e32 v242, v5, v11
	s_nop 0
	v_cndmask_b32_e64 v5, v5, v11, s[4:5]
	v_cndmask_b32_e32 v5, v5, v242, vcc
	v_cmp_ne_u32_e32 vcc, v196, v5
	s_nop 1
	v_cndmask_b32_e32 v8, -1.0, v8, vcc
	v_cmp_ne_u32_e32 vcc, v199, v5
	s_nop 1
	v_cndmask_b32_e32 v9, -1.0, v9, vcc
	v_cmp_ne_u32_e32 vcc, v200, v5
	s_nop 1
	v_cndmask_b32_e32 v10, -1.0, v6, vcc
	v_cmp_ne_u32_e32 vcc, v201, v5
	s_nop 1
	v_cndmask_b32_e32 v7, -1.0, v7, vcc
	v_cmp_gt_f32_e32 vcc, v9, v8
	s_nop 1
	v_cndmask_b32_e32 v6, v8, v9, vcc
	s_waitcnt lgkmcnt(0)
	v_cndmask_b32_e32 v11, v196, v199, vcc
	v_cmp_gt_f32_e32 vcc, v10, v6
	s_nop 1
	v_cndmask_b32_e32 v6, v6, v10, vcc
	v_cndmask_b32_e32 v13, v11, v200, vcc
	v_cmp_gt_f32_e32 vcc, v7, v6
	s_nop 1
	v_cndmask_b32_e32 v11, v6, v7, vcc
	s_nop 1
	v_mov_b32_dpp v12, v11 quad_perm:[1,0,3,2] row_mask:0xf bank_mask:0xf
	v_cndmask_b32_e32 v6, v13, v201, vcc
	s_nop 1
	v_mov_b32_dpp v13, v6 quad_perm:[1,0,3,2] row_mask:0xf bank_mask:0xf
	s_waitcnt lgkmcnt(1)
	v_cmp_lt_f32_e64 s[4:5], v11, v12
	v_cmp_eq_f32_e32 vcc, v11, v12
	s_waitcnt lgkmcnt(0)
	v_min_i32_e32 v242, v6, v13
	v_cndmask_b32_e64 v11, v11, v12, s[4:5]
	v_cndmask_b32_e64 v6, v6, v13, s[4:5]
	v_cndmask_b32_e32 v6, v6, v242, vcc
	s_waitcnt lgkmcnt(0)
	s_nop 1
	v_mov_b32_dpp v13, v11 quad_perm:[2,3,0,1] row_mask:0xf bank_mask:0xf
	s_nop 1
	v_mov_b32_dpp v12, v6 quad_perm:[2,3,0,1] row_mask:0xf bank_mask:0xf
	s_waitcnt lgkmcnt(1)
	v_cmp_lt_f32_e64 s[4:5], v11, v13
	v_cmp_eq_f32_e32 vcc, v11, v13
	s_waitcnt lgkmcnt(0)
	v_min_i32_e32 v242, v6, v12
	v_cndmask_b32_e64 v11, v11, v13, s[4:5]
	v_cndmask_b32_e64 v6, v6, v12, s[4:5]
	v_cndmask_b32_e32 v6, v6, v242, vcc
	s_nop 1
	v_mov_b32_dpp v241, v11 row_half_mirror row_mask:0xf bank_mask:0xf
	s_nop 1
	v_mov_b32_dpp v13, v241 quad_perm:[3,2,1,0] row_mask:0xf bank_mask:0xf
	s_waitcnt lgkmcnt(1)
	s_nop 1
	v_mov_b32_dpp v241, v6 row_half_mirror row_mask:0xf bank_mask:0xf
	s_nop 1
	v_mov_b32_dpp v12, v241 quad_perm:[3,2,1,0] row_mask:0xf bank_mask:0xf
	s_waitcnt lgkmcnt(1)
	v_cmp_lt_f32_e64 s[4:5], v11, v13
	v_cmp_eq_f32_e32 vcc, v11, v13
	s_waitcnt lgkmcnt(0)
	v_min_i32_e32 v242, v6, v12
	s_nop 0
	v_cndmask_b32_e64 v6, v6, v12, s[4:5]
	v_cndmask_b32_e32 v6, v6, v242, vcc
	v_cmp_ne_u32_e32 vcc, v196, v6
	s_nop 1
	v_cndmask_b32_e32 v8, -1.0, v8, vcc
	v_cmp_ne_u32_e32 vcc, v199, v6
	s_nop 1
	v_cndmask_b32_e32 v9, -1.0, v9, vcc
	v_cmp_ne_u32_e32 vcc, v200, v6
	s_nop 1
	v_cndmask_b32_e32 v10, -1.0, v10, vcc
	v_cmp_ne_u32_e32 vcc, v201, v6
	s_nop 1
	v_cndmask_b32_e32 v7, -1.0, v7, vcc
	v_cmp_gt_f32_e32 vcc, v9, v8
	s_nop 1
	v_cndmask_b32_e32 v8, v8, v9, vcc
	v_cndmask_b32_e32 v9, v196, v199, vcc
	v_cmp_gt_f32_e32 vcc, v10, v8
	s_nop 1
	v_cndmask_b32_e32 v8, v8, v10, vcc
	v_cndmask_b32_e32 v10, v9, v200, vcc
	v_cmp_gt_f32_e32 vcc, v7, v8
	s_nop 1
	v_cndmask_b32_e32 v8, v8, v7, vcc
	s_nop 1
	v_mov_b32_dpp v9, v8 quad_perm:[1,0,3,2] row_mask:0xf bank_mask:0xf
	v_cndmask_b32_e32 v7, v10, v201, vcc
	s_nop 1
	v_mov_b32_dpp v1, v7 quad_perm:[1,0,3,2] row_mask:0xf bank_mask:0xf
	s_waitcnt lgkmcnt(1)
	v_cmp_lt_f32_e64 s[4:5], v8, v9
	v_cmp_eq_f32_e32 vcc, v8, v9
	s_waitcnt lgkmcnt(0)
	v_min_i32_e32 v242, v7, v1
	v_cndmask_b32_e64 v8, v8, v9, s[4:5]
	v_cndmask_b32_e64 v7, v7, v1, s[4:5]
	v_cndmask_b32_e32 v7, v7, v242, vcc
	s_nop 1
	v_mov_b32_dpp v9, v8 quad_perm:[2,3,0,1] row_mask:0xf bank_mask:0xf
	s_waitcnt lgkmcnt(1)
	s_nop 1
	v_mov_b32_dpp v1, v7 quad_perm:[2,3,0,1] row_mask:0xf bank_mask:0xf
	s_waitcnt lgkmcnt(1)
	v_cmp_lt_f32_e64 s[4:5], v8, v9
	v_cmp_eq_f32_e32 vcc, v8, v9
	s_waitcnt lgkmcnt(0)
	v_min_i32_e32 v242, v7, v1
	v_cndmask_b32_e64 v8, v8, v9, s[4:5]
	v_cndmask_b32_e64 v7, v7, v1, s[4:5]
	v_cndmask_b32_e32 v7, v7, v242, vcc
	s_nop 1
	v_mov_b32_dpp v241, v8 row_half_mirror row_mask:0xf bank_mask:0xf
	s_nop 1
	v_mov_b32_dpp v2, v241 quad_perm:[3,2,1,0] row_mask:0xf bank_mask:0xf
	s_waitcnt lgkmcnt(1)
	s_nop 1
	v_mov_b32_dpp v241, v7 row_half_mirror row_mask:0xf bank_mask:0xf
	s_nop 1
	v_mov_b32_dpp v1, v241 quad_perm:[3,2,1,0] row_mask:0xf bank_mask:0xf
	s_waitcnt lgkmcnt(1)
	v_cmp_lt_f32_e64 s[4:5], v8, v2
	v_cmp_eq_f32_e32 vcc, v8, v2
	s_waitcnt lgkmcnt(0)
	v_min_i32_e32 v242, v7, v1
	s_nop 0
	v_cndmask_b32_e64 v7, v7, v1, s[4:5]
	v_cndmask_b32_e32 v7, v7, v242, vcc
	s_add_i32 s3, s93, -1
	s_lshl_b32 s2, 1, s93
	s_lshl_b32 s3, 1, s3
	v_lshlrev_b32_e64 v3, v4, 1
	v_lshlrev_b32_e64 v0, v0, 1
	s_or_b32 s2, s2, s3
	s_waitcnt lgkmcnt(0)
	v_lshlrev_b32_e64 v1, v6, 1
	v_lshlrev_b32_e64 v2, v5, 1
	v_or3_b32 v0, s2, v0, v3
	v_lshlrev_b32_e64 v4, v7, 1
	v_or3_b32 v0, v0, v2, v1
	v_or3_b32 v0, v0, v4, 1
	s_mov_b64 s[4:5], 0
